# load balance: Fourier step-A/step-B tiles only on the 448 half-blocks without a fifth RG-LRU tile (stride 448)
# baseline (speedup 1.0000x reference)
; template <bool BNN, class AL, class BL>
; __device__ __forceinline__ void gemm_tile(const AL& al, const BL& bl, int K, u16* smem, f32x16 (&acc)[2][2]) {
;     ...
;   G_LOAD(ra0, rb0, 0)
;   G_STORE(ra0, rb0, 0)
;   if (nkt > 1) G_LOAD(ra1, rb1, 1)
;   __syncthreads();
;   for (int kt = 0; kt < nkt; kt += 2) {
;     if (kt + 2 < nkt) G_LOAD(ra0, rb0, kt + 2)
;     G_COMPUTE(0)
;     if (kt + 1 < nkt) G_STORE(ra1, rb1, 1)
;     __syncthreads();
;     if (kt + 1 >= nkt) break;
;     if (kt + 3 < nkt) G_LOAD(ra1, rb1, kt + 3)
;     G_COMPUTE(1)
;     if (kt + 2 < nkt) G_STORE(ra0, rb0, 0)
;     __syncthreads();
; __device__ __forceinline__ void fourier_stepA_tile(const Params& P, int t, u16* smem) {
;   const int mt = t >> 3, grp = t & 7;
;   const u16* Ab = P.zq + (long)mt * 128 * 1536 + 1024 + grp * 64;
;   const u16* Bb = P.d64t;
;   auto al = [=](int r, int k) { return ldg16(Ab + (unsigned)(r * 1536 + k)); };
;   auto bl = [=](int r, int k) { return ldg16(Bb + r * 64 + k); };
;   f32x16 acc[2][2];
;   gemm_tile<false>(al, bl, 64, smem, acc);
;   u16* G = P.zq + (long)N_TOK * 1536 + (long)mt * 128 * 1024 + grp * 64;
;   ACC_FOREACH({ G[(unsigned)(row * 1024 + (col >> 6) * 512 + (col & 63))] = f2bf(v); })
; }
.LBB0_417:
	s_or_b64 exec, exec, s[8:9]
	v_readfirstlane_b32 s0, v86
	v_subrev_u32_e32 v86, 64, v86
	s_nop 1
	s_cmp_lt_u32 s0, 64
	s_cbranch_scc1 .LBB0_419
	v_mul_u32_u24_e32 v1, 0x600, v72
	s_movk_i32 s0, 0x48
	v_or_b32_e32 v8, v1, v48
	v_mad_u32_u24 v1, v69, s0, v48
	v_and_b32_e32 v3, 8, v66
	v_lshl_add_u32 v89, v1, 1, v49
	v_and_b32_e32 v1, 31, v152
	v_lshlrev_b32_e32 v3, 1, v3
	v_and_or_b32 v1, v64, 64, v1
	v_add_u32_e32 v5, v49, v3
	s_movk_i32 s0, 0x90
	v_mov_b32_e32 v65, 0
	v_lshlrev_b32_e32 v4, 7, v69
	v_mad_u32_u24 v90, v1, s0, v5
	v_and_b32_e32 v1, 0x5f, v152
	v_lshlrev_b32_e32 v64, 1, v48
	v_mul_u32_u24_e32 v0, 0x600, v69
	v_mul_u32_u24_e32 v1, 0x48, v1
	v_lshl_add_u64 v[10:11], s[42:43], 0, v[64:65]
	v_or_b32_e32 v64, 0x1000, v4
	v_or_b32_e32 v0, v0, v48
	v_lshlrev_b32_e32 v1, 1, v1
	v_lshl_add_u64 v[68:69], v[10:11], 0, v[64:65]
	v_or_b32_e32 v64, 0x2000, v4
	v_add_u32_e32 v2, 0xc000, v0
	v_add_u32_e32 v6, 0x18000, v0
	v_add3_u32 v91, v49, v1, v3
	v_add_u32_e32 v92, v5, v1
	v_mov_b32_e32 v5, v65
	v_lshl_add_u64 v[70:71], v[10:11], 0, v[64:65]
	v_lshlrev_b32_e32 v64, 7, v72
	s_add_u32 s0, s90, 0x6300000
	v_lshlrev_b32_e32 v1, 6, v153
	v_lshl_add_u64 v[66:67], v[10:11], 0, v[4:5]
	v_lshl_add_u64 v[72:73], v[10:11], 0, v[64:65]
	s_addc_u32 s1, s91, 0
	v_lshl_add_u32 v93, s2, 7, v1
	s_lshl_b32 s8, s96, 7
	s_mov_b64 s[4:5], 0
	s_mov_b32 s9, 0x60000
	v_mov_b64_e32 v[74:75], s[90:91]
	v_lshlrev_b32_e32 v76, 1, v0
	v_mov_b32_e32 v77, v65
	v_lshlrev_b32_e32 v78, 1, v2
	v_mov_b32_e32 v79, v65
	v_lshlrev_b32_e32 v80, 1, v6
	v_mov_b32_e32 v81, v65
	v_lshlrev_b32_e32 v82, 1, v8
	v_mov_b32_e32 v83, v65
	s_movk_i32 s10, 0x200
	s_mov_b32 s11, 0x3fffc0
	s_movk_i32 s12, 0x83f
.LBB0_418:
	v_ashrrev_i32_e32 v84, 3, v86
	v_and_b32_e32 v2, 0x1c0, v93
	v_mad_i64_i32 v[0:1], s[14:15], v84, s9, v[74:75]
	v_lshlrev_b32_e32 v64, 1, v2
	v_lshl_add_u64 v[0:1], v[0:1], 0, v[64:65]
	v_lshl_add_u64 v[12:13], v[0:1], 0, v[76:77]
	v_lshl_add_u64 v[16:17], v[0:1], 0, v[78:79]
	v_lshl_add_u64 v[20:21], v[0:1], 0, v[80:81]
	v_lshl_add_u64 v[24:25], v[0:1], 0, v[82:83]
	global_load_dwordx4 v[0:3], v[66:67], off
	global_load_dwordx4 v[4:7], v[68:69], off
	global_load_dwordx4 v[8:11], v[70:71], off
	s_nop 0
	global_load_dwordx4 v[12:15], v[12:13], off offset:2048
	s_nop 0
	global_load_dwordx4 v[16:19], v[16:17], off offset:2048
	s_nop 0
	global_load_dwordx4 v[20:23], v[20:21], off offset:2048
	s_nop 0
	global_load_dwordx4 v[24:27], v[24:25], off offset:2048
	s_nop 0
	global_load_dwordx4 v[28:31], v[72:73], off
	v_ashrrev_i32_e32 v85, 31, v84
	s_waitcnt vmcnt(7)
	ds_write_b128 v89, v[0:3] offset:36864
	s_waitcnt vmcnt(6)
	ds_write_b128 v89, v[4:7] offset:41472
	s_waitcnt vmcnt(5)
	ds_write_b128 v89, v[8:11] offset:46080
	s_waitcnt vmcnt(4)
	ds_write_b128 v89, v[12:15]
	s_waitcnt vmcnt(3)
	ds_write_b128 v89, v[16:19] offset:4608
	s_waitcnt vmcnt(2)
	ds_write_b128 v89, v[20:23] offset:9216
	s_waitcnt vmcnt(1)
	ds_write_b128 v88, v[24:27]
	s_waitcnt vmcnt(0)
	ds_write_b128 v88, v[28:31] offset:36864
	s_waitcnt lgkmcnt(0)
	s_barrier
	ds_read_b128 v[0:3], v90
	ds_read_b128 v[4:7], v91 offset:36864
	ds_read_b128 v[8:11], v91 offset:41472
	ds_read_b128 v[94:97], v90 offset:32
	s_waitcnt lgkmcnt(2)
	v_mfma_f32_32x32x16_bf16 v[48:63], v[0:3], v[4:7], 0
	s_waitcnt lgkmcnt(1)
	v_mfma_f32_32x32x16_bf16 v[32:47], v[0:3], v[8:11], 0
	ds_read_b128 v[0:3], v90 offset:4608
	ds_read_b128 v[98:101], v90 offset:4640
	ds_read_b128 v[102:105], v92 offset:36896
	ds_read_b128 v[106:109], v92 offset:41504
	s_waitcnt lgkmcnt(3)
	v_mfma_f32_32x32x16_bf16 v[16:31], v[0:3], v[4:7], 0
	v_mfma_f32_32x32x16_bf16 v[0:15], v[0:3], v[8:11], 0
	s_waitcnt lgkmcnt(1)
	v_mfma_f32_32x32x16_bf16 v[48:63], v[94:97], v[102:105], v[48:63]
	s_waitcnt lgkmcnt(0)
	v_mfma_f32_32x32x16_bf16 v[32:47], v[94:97], v[106:109], v[32:47]
	v_mfma_f32_32x32x16_bf16 v[16:31], v[98:101], v[102:105], v[16:31]
	ds_read_b128 v[94:97], v90 offset:64
	ds_read_b128 v[102:105], v90 offset:4672
	ds_read_b128 v[110:113], v92 offset:36928
	ds_read_b128 v[114:117], v92 offset:41536
	v_mfma_f32_32x32x16_bf16 v[0:15], v[98:101], v[106:109], v[0:15]
	s_waitcnt lgkmcnt(1)
	v_mfma_f32_32x32x16_bf16 v[48:63], v[94:97], v[110:113], v[48:63]
	s_waitcnt lgkmcnt(0)
	v_mfma_f32_32x32x16_bf16 v[32:47], v[94:97], v[114:117], v[32:47]
	v_mfma_f32_32x32x16_bf16 v[16:31], v[102:105], v[110:113], v[16:31]
	ds_read_b128 v[94:97], v90 offset:96
	ds_read_b128 v[98:101], v90 offset:4704
	ds_read_b128 v[106:109], v92 offset:36960
	ds_read_b128 v[110:113], v92 offset:41568
	v_mfma_f32_32x32x16_bf16 v[0:15], v[102:105], v[114:117], v[0:15]
	v_lshlrev_b64 v[84:85], 18, v[84:85]
	s_waitcnt lgkmcnt(1)
	v_mfma_f32_32x32x16_bf16 v[48:63], v[94:97], v[106:109], v[48:63]
	v_lshl_add_u64 v[84:85], s[0:1], 0, v[84:85]
	v_lshl_add_u64 v[84:85], v[84:85], 0, v[64:65]
	v_mov_b32_e32 v64, v87
	s_waitcnt lgkmcnt(0)
	s_barrier
; __device__ __forceinline__ void fourier_stepA_tile(const Params& P, int t, u16* smem) {
;     ...
;   u16* G = P.zq + (long)N_TOK * 1536 + (long)mt * 128 * 1024 + grp * 64;
;   ACC_FOREACH({ G[(unsigned)(row * 1024 + (col >> 6) * 512 + (col & 63))] = f2bf(v); })
	v_mfma_f32_32x32x16_bf16 v[32:47], v[94:97], v[110:113], v[32:47]
	v_lshrrev_b32_e32 v103, 3, v64
	v_lshrrev_b32_e32 v102, 1, v64
	v_and_b32_e32 v103, 4, v103
	v_lshlrev_b32_e32 v104, 3, v64
	v_and_b32_e32 v64, 31, v64
	v_and_or_b32 v96, v104, s10, v64
	v_and_or_b32 v64, v102, s11, v103
	v_lshlrev_b32_e32 v97, 10, v64
	v_or_b32_e32 v64, v97, v96
	v_cvt_pk_bf16_f32 v48, v48, s0
	v_lshl_add_u64 v[94:95], v[64:65], 1, v[84:85]
	v_or_b32_e32 v102, 0x800, v97
	global_store_short v[94:95], v48, off
	v_cvt_pk_bf16_f32 v48, v49, s0
	v_or_b32_e32 v64, v102, v96
	global_store_short v[94:95], v48, off offset:2048
	v_cvt_pk_bf16_f32 v50, v50, s0
	v_lshl_add_u64 v[48:49], v[64:65], 1, v[84:85]
	global_store_short v[48:49], v50, off
	v_cvt_pk_bf16_f32 v50, v51, s0
	v_or_b32_e32 v51, 0xc00, v97
	v_or_b32_e32 v64, v51, v96
	v_lshl_add_u64 v[48:49], v[64:65], 1, v[84:85]
	global_store_short v[48:49], v50, off
	v_cvt_pk_bf16_f32 v50, v52, s0
	v_or_b32_e32 v52, 0x2000, v97
	v_or_b32_e32 v64, v52, v96
	v_lshl_add_u64 v[48:49], v[64:65], 1, v[84:85]
	global_store_short v[48:49], v50, off
	v_cvt_pk_bf16_f32 v50, v53, s0
	v_or_b32_e32 v53, 0x2400, v97
	v_or_b32_e32 v64, v53, v96
	v_lshl_add_u64 v[48:49], v[64:65], 1, v[84:85]
	global_store_short v[48:49], v50, off
	v_cvt_pk_bf16_f32 v50, v54, s0
	v_or_b32_e32 v54, 0x2800, v97
	v_or_b32_e32 v64, v54, v96
	v_lshl_add_u64 v[48:49], v[64:65], 1, v[84:85]
	global_store_short v[48:49], v50, off
	v_cvt_pk_bf16_f32 v50, v55, s0
	v_or_b32_e32 v55, 0x2c00, v97
	v_or_b32_e32 v64, v55, v96
	v_lshl_add_u64 v[48:49], v[64:65], 1, v[84:85]
	global_store_short v[48:49], v50, off
	v_cvt_pk_bf16_f32 v50, v56, s0
	v_or_b32_e32 v56, 0x4000, v97
	v_or_b32_e32 v64, v56, v96
	v_lshl_add_u64 v[48:49], v[64:65], 1, v[84:85]
	global_store_short v[48:49], v50, off
	v_cvt_pk_bf16_f32 v50, v57, s0
	v_or_b32_e32 v57, 0x4400, v97
	v_or_b32_e32 v64, v57, v96
	v_lshl_add_u64 v[48:49], v[64:65], 1, v[84:85]
	global_store_short v[48:49], v50, off
	v_cvt_pk_bf16_f32 v50, v58, s0
	v_or_b32_e32 v58, 0x4800, v97
	v_or_b32_e32 v64, v58, v96
	v_lshl_add_u64 v[48:49], v[64:65], 1, v[84:85]
	global_store_short v[48:49], v50, off
	v_cvt_pk_bf16_f32 v50, v59, s0
	v_or_b32_e32 v59, 0x4c00, v97
	v_or_b32_e32 v64, v59, v96
	v_lshl_add_u64 v[48:49], v[64:65], 1, v[84:85]
	global_store_short v[48:49], v50, off
	v_cvt_pk_bf16_f32 v50, v60, s0
	v_or_b32_e32 v60, 0x6000, v97
	v_or_b32_e32 v64, v60, v96
	v_lshl_add_u64 v[48:49], v[64:65], 1, v[84:85]
	global_store_short v[48:49], v50, off
	v_cvt_pk_bf16_f32 v50, v61, s0
	v_or_b32_e32 v61, 0x6400, v97
	v_or_b32_e32 v64, v61, v96
	v_lshl_add_u64 v[48:49], v[64:65], 1, v[84:85]
	global_store_short v[48:49], v50, off
	v_cvt_pk_bf16_f32 v50, v62, s0
	v_or_b32_e32 v62, 0x6800, v97
	v_or_b32_e32 v64, v62, v96
	v_lshl_add_u64 v[48:49], v[64:65], 1, v[84:85]
	global_store_short v[48:49], v50, off
	v_cvt_pk_bf16_f32 v50, v63, s0
	v_or_b32_e32 v63, 0x6c00, v97
	v_or_b32_e32 v64, v63, v96
	v_lshl_add_u64 v[48:49], v[64:65], 1, v[84:85]
	global_store_short v[48:49], v50, off
	v_or_b32_e32 v48, 32, v96
	v_cvt_pk_bf16_f32 v32, v32, s0
	v_or_b32_e32 v64, v97, v48
	global_store_short v[94:95], v32, off offset:64
	v_cvt_pk_bf16_f32 v49, v33, s0
	v_lshl_add_u64 v[32:33], v[64:65], 1, v[84:85]
	v_or_b32_e32 v64, v102, v48
	global_store_short v[32:33], v49, off offset:2048
	v_cvt_pk_bf16_f32 v34, v34, s0
	v_lshl_add_u64 v[32:33], v[64:65], 1, v[84:85]
	v_or_b32_e32 v64, v51, v48
	global_store_short v[32:33], v34, off
	v_cvt_pk_bf16_f32 v34, v35, s0
	v_lshl_add_u64 v[32:33], v[64:65], 1, v[84:85]
	v_or_b32_e32 v64, v52, v48
	global_store_short v[32:33], v34, off
	v_cvt_pk_bf16_f32 v34, v36, s0
	v_lshl_add_u64 v[32:33], v[64:65], 1, v[84:85]
	v_or_b32_e32 v64, v53, v48
	global_store_short v[32:33], v34, off
	v_cvt_pk_bf16_f32 v34, v37, s0
	v_lshl_add_u64 v[32:33], v[64:65], 1, v[84:85]
	v_or_b32_e32 v64, v54, v48
	global_store_short v[32:33], v34, off
	v_cvt_pk_bf16_f32 v34, v38, s0
	v_lshl_add_u64 v[32:33], v[64:65], 1, v[84:85]
	v_or_b32_e32 v64, v55, v48
	global_store_short v[32:33], v34, off
	v_cvt_pk_bf16_f32 v34, v39, s0
	v_lshl_add_u64 v[32:33], v[64:65], 1, v[84:85]
	v_or_b32_e32 v64, v56, v48
	global_store_short v[32:33], v34, off
	v_cvt_pk_bf16_f32 v34, v40, s0
	v_lshl_add_u64 v[32:33], v[64:65], 1, v[84:85]
	v_or_b32_e32 v64, v57, v48
	global_store_short v[32:33], v34, off
	v_cvt_pk_bf16_f32 v34, v41, s0
	v_lshl_add_u64 v[32:33], v[64:65], 1, v[84:85]
	v_or_b32_e32 v64, v58, v48
	v_mfma_f32_32x32x16_bf16 v[16:31], v[98:101], v[106:109], v[16:31]
	global_store_short v[32:33], v34, off
	v_cvt_pk_bf16_f32 v34, v42, s0
	v_lshl_add_u64 v[32:33], v[64:65], 1, v[84:85]
	v_or_b32_e32 v64, v59, v48
	global_store_short v[32:33], v34, off
	v_cvt_pk_bf16_f32 v34, v43, s0
	v_lshl_add_u64 v[32:33], v[64:65], 1, v[84:85]
	v_or_b32_e32 v64, v60, v48
	global_store_short v[32:33], v34, off
	v_cvt_pk_bf16_f32 v34, v44, s0
	v_lshl_add_u64 v[32:33], v[64:65], 1, v[84:85]
	v_or_b32_e32 v64, v61, v48
	global_store_short v[32:33], v34, off
	v_cvt_pk_bf16_f32 v34, v45, s0
	v_lshl_add_u64 v[32:33], v[64:65], 1, v[84:85]
	v_or_b32_e32 v64, v62, v48
	global_store_short v[32:33], v34, off
	v_cvt_pk_bf16_f32 v34, v46, s0
	v_lshl_add_u64 v[32:33], v[64:65], 1, v[84:85]
	v_or_b32_e32 v64, v63, v48
	global_store_short v[32:33], v34, off
	v_cvt_pk_bf16_f32 v34, v47, s0
	v_lshl_add_u64 v[32:33], v[64:65], 1, v[84:85]
; __device__ __forceinline__ void fourier_stepA_tile(const Params& P, int t, u16* smem) {
;     ...
;   u16* G = P.zq + (long)N_TOK * 1536 + (long)mt * 128 * 1024 + grp * 64;
;   ACC_FOREACH({ G[(unsigned)(row * 1024 + (col >> 6) * 512 + (col & 63))] = f2bf(v); })
; __device__ __forceinline__ void run_phase(const Params& P, const int ph, char* smem_raw) {
;     ...
;       for (int t = VBID; t < 2112; t += VGRID) lru_tile(P, t >> 3, t & 7, 1, smv_raw);
;       for (int t = VBID; t < 2112; t += VGRID) fourier_stepA_tile(P, t, smv);
	global_store_short v[32:33], v34, off
	v_or_b32_e32 v34, 0x8000, v97
	v_or_b32_e32 v64, v34, v96
	v_cvt_pk_bf16_f32 v16, v16, s0
	v_lshl_add_u64 v[32:33], v[64:65], 1, v[84:85]
	global_store_short v[32:33], v16, off
	v_or_b32_e32 v33, 0x8400, v97
	v_or_b32_e32 v64, v33, v96
	v_cvt_pk_bf16_f32 v32, v17, s0
	v_lshl_add_u64 v[16:17], v[64:65], 1, v[84:85]
	global_store_short v[16:17], v32, off
	v_or_b32_e32 v32, 0x8800, v97
	v_or_b32_e32 v64, v32, v96
	v_cvt_pk_bf16_f32 v18, v18, s0
	v_lshl_add_u64 v[16:17], v[64:65], 1, v[84:85]
	global_store_short v[16:17], v18, off
	v_cvt_pk_bf16_f32 v18, v19, s0
	v_or_b32_e32 v19, 0x8c00, v97
	v_or_b32_e32 v64, v19, v96
	v_lshl_add_u64 v[16:17], v[64:65], 1, v[84:85]
	global_store_short v[16:17], v18, off
	v_cvt_pk_bf16_f32 v18, v20, s0
	v_or_b32_e32 v20, 0xa000, v97
	v_or_b32_e32 v64, v20, v96
	v_lshl_add_u64 v[16:17], v[64:65], 1, v[84:85]
	global_store_short v[16:17], v18, off
	v_cvt_pk_bf16_f32 v18, v21, s0
	v_or_b32_e32 v21, 0xa400, v97
	v_or_b32_e32 v64, v21, v96
	v_lshl_add_u64 v[16:17], v[64:65], 1, v[84:85]
	global_store_short v[16:17], v18, off
	v_cvt_pk_bf16_f32 v18, v22, s0
	v_or_b32_e32 v22, 0xa800, v97
	v_or_b32_e32 v64, v22, v96
	v_lshl_add_u64 v[16:17], v[64:65], 1, v[84:85]
	global_store_short v[16:17], v18, off
	v_cvt_pk_bf16_f32 v18, v23, s0
	v_or_b32_e32 v23, 0xac00, v97
	v_or_b32_e32 v64, v23, v96
	v_lshl_add_u64 v[16:17], v[64:65], 1, v[84:85]
	global_store_short v[16:17], v18, off
	v_cvt_pk_bf16_f32 v18, v24, s0
	v_or_b32_e32 v24, 0xc000, v97
	v_or_b32_e32 v64, v24, v96
	v_lshl_add_u64 v[16:17], v[64:65], 1, v[84:85]
	global_store_short v[16:17], v18, off
	v_cvt_pk_bf16_f32 v18, v25, s0
	v_or_b32_e32 v25, 0xc400, v97
	v_or_b32_e32 v64, v25, v96
	v_lshl_add_u64 v[16:17], v[64:65], 1, v[84:85]
	global_store_short v[16:17], v18, off
	v_cvt_pk_bf16_f32 v18, v26, s0
	v_or_b32_e32 v26, 0xc800, v97
	v_or_b32_e32 v64, v26, v96
	v_lshl_add_u64 v[16:17], v[64:65], 1, v[84:85]
	global_store_short v[16:17], v18, off
	v_cvt_pk_bf16_f32 v18, v27, s0
	v_or_b32_e32 v27, 0xcc00, v97
	v_or_b32_e32 v64, v27, v96
	v_lshl_add_u64 v[16:17], v[64:65], 1, v[84:85]
	global_store_short v[16:17], v18, off
	v_cvt_pk_bf16_f32 v18, v28, s0
	v_or_b32_e32 v28, 0xe000, v97
	v_or_b32_e32 v64, v28, v96
	v_lshl_add_u64 v[16:17], v[64:65], 1, v[84:85]
	global_store_short v[16:17], v18, off
	v_cvt_pk_bf16_f32 v18, v29, s0
	v_or_b32_e32 v29, 0xe400, v97
	v_mfma_f32_32x32x16_bf16 v[0:15], v[98:101], v[110:113], v[0:15]
	v_or_b32_e32 v64, v29, v96
	v_lshl_add_u64 v[16:17], v[64:65], 1, v[84:85]
	global_store_short v[16:17], v18, off
	v_cvt_pk_bf16_f32 v18, v30, s0
	v_or_b32_e32 v30, 0xe800, v97
	v_or_b32_e32 v64, v30, v96
	v_lshl_add_u64 v[16:17], v[64:65], 1, v[84:85]
	global_store_short v[16:17], v18, off
	v_cvt_pk_bf16_f32 v18, v31, s0
	v_or_b32_e32 v31, 0xec00, v97
	v_or_b32_e32 v64, v31, v96
	v_lshl_add_u64 v[16:17], v[64:65], 1, v[84:85]
	v_or_b32_e32 v64, v34, v48
	global_store_short v[16:17], v18, off
	v_cvt_pk_bf16_f32 v0, v0, s0
	v_lshl_add_u64 v[16:17], v[64:65], 1, v[84:85]
	v_or_b32_e32 v64, v33, v48
	global_store_short v[16:17], v0, off
	v_cvt_pk_bf16_f32 v16, v1, s0
	v_lshl_add_u64 v[0:1], v[64:65], 1, v[84:85]
	v_or_b32_e32 v64, v32, v48
	global_store_short v[0:1], v16, off
	v_cvt_pk_bf16_f32 v2, v2, s0
	v_lshl_add_u64 v[0:1], v[64:65], 1, v[84:85]
	v_or_b32_e32 v64, v19, v48
	global_store_short v[0:1], v2, off
	v_cvt_pk_bf16_f32 v2, v3, s0
	v_lshl_add_u64 v[0:1], v[64:65], 1, v[84:85]
	v_or_b32_e32 v64, v20, v48
	global_store_short v[0:1], v2, off
	v_cvt_pk_bf16_f32 v2, v4, s0
	v_lshl_add_u64 v[0:1], v[64:65], 1, v[84:85]
	v_or_b32_e32 v64, v21, v48
	global_store_short v[0:1], v2, off
	v_cvt_pk_bf16_f32 v2, v5, s0
	v_lshl_add_u64 v[0:1], v[64:65], 1, v[84:85]
	v_or_b32_e32 v64, v22, v48
	global_store_short v[0:1], v2, off
	v_cvt_pk_bf16_f32 v2, v6, s0
	v_lshl_add_u64 v[0:1], v[64:65], 1, v[84:85]
	v_or_b32_e32 v64, v23, v48
	global_store_short v[0:1], v2, off
	v_cvt_pk_bf16_f32 v2, v7, s0
	v_lshl_add_u64 v[0:1], v[64:65], 1, v[84:85]
	v_or_b32_e32 v64, v24, v48
	global_store_short v[0:1], v2, off
	v_cvt_pk_bf16_f32 v2, v8, s0
	v_lshl_add_u64 v[0:1], v[64:65], 1, v[84:85]
	v_or_b32_e32 v64, v25, v48
	global_store_short v[0:1], v2, off
	v_cvt_pk_bf16_f32 v2, v9, s0
	v_lshl_add_u64 v[0:1], v[64:65], 1, v[84:85]
	v_or_b32_e32 v64, v26, v48
	global_store_short v[0:1], v2, off
	v_cvt_pk_bf16_f32 v2, v10, s0
	v_lshl_add_u64 v[0:1], v[64:65], 1, v[84:85]
	v_or_b32_e32 v64, v27, v48
	global_store_short v[0:1], v2, off
	v_cvt_pk_bf16_f32 v2, v11, s0
	v_lshl_add_u64 v[0:1], v[64:65], 1, v[84:85]
	v_or_b32_e32 v64, v28, v48
	global_store_short v[0:1], v2, off
	v_cvt_pk_bf16_f32 v2, v12, s0
	v_lshl_add_u64 v[0:1], v[64:65], 1, v[84:85]
	v_or_b32_e32 v64, v29, v48
	global_store_short v[0:1], v2, off
	v_cvt_pk_bf16_f32 v2, v13, s0
	v_lshl_add_u64 v[0:1], v[64:65], 1, v[84:85]
	v_or_b32_e32 v64, v30, v48
	v_add_u32_e32 v86, 0x1c0, v86
	global_store_short v[0:1], v2, off
	v_cvt_pk_bf16_f32 v2, v14, s0
	v_lshl_add_u64 v[0:1], v[64:65], 1, v[84:85]
	v_or_b32_e32 v64, v31, v48
	v_cmp_lt_i32_e32 vcc, s12, v86
	global_store_short v[0:1], v2, off
	v_cvt_pk_bf16_f32 v2, v15, s0
	v_lshl_add_u64 v[0:1], v[64:65], 1, v[84:85]
	s_or_b64 s[4:5], vcc, s[4:5]
	v_add_u32_e32 v93, s8, v93
	global_store_short v[0:1], v2, off
	s_andn2_b64 exec, exec, s[4:5]
	s_cbranch_execnz .LBB0_418

; __device__ __forceinline__ void nn_phase(const Params& P, int set, u16* smem) {
;   const int nT = (set == 0) ? 2080 : 1024;
;   for (int t = VBID; t < nT; t += VGRID) {
;     const u16 *Ab, *Bb; u16* Cb; unsigned lda, s1, s2, e1, e2; int K;
;     const u16* G = P.zq + (long)N_TOK * 1536;
;     const int nt = t & 3;
;     if (set == 0 && t < 2048) {
;       const int bt = t >> 2, t2 = bt & 127, b = bt >> 7;
;       Ab = P.sbm + (long)t2 * 128 * 128; lda = 128; K = 128;
;       Bb = G + ((long)b * 8192 + t2) * 1024 + nt * 128; s1 = 512; s2 = 128 * 1024;
;       Cb = P.zf + (long)b * 64 * 256 * 512 + (long)t2 * 512 + nt * 128; e1 = 128 * 512; e2 = 256 * 512;
;     } else if (set == 0) {
;       const int tt = t - 2048, mt = (tt >> 2) & 1, b = tt >> 3;
;       Ab = P.sxm + (long)mt * 128 * 512; lda = 512; K = 512;
;       Bb = G + ((long)N_X + b * 256) * 1024 + nt * 128; s1 = 512; s2 = 1024;
;       Cb = P.cat + ((long)N_X + b * 256 + mt * 128) * 1024 + 512 + nt * 128; e1 = 1024; e2 = 2048;
;     } else {
;       const int bk = t >> 2, k1 = bk & 63, b = bk >> 6;
;       Ab = P.scm; lda = 256; K = 256;
;       Bb = P.zf + ((long)b * 64 + k1) * 256 * 512 + nt * 128; s1 = 512; s2 = 1024;
;       Cb = P.cat + ((long)b * 8192 + k1) * 1024 + 512 + nt * 128; e1 = 64 * 1024; e2 = 128 * 1024;
;     }
.LBB0_680:
	s_or_b64 exec, exec, s[16:17]
	v_subrev_u32_e32 v74, 64, v74
	s_movk_i32 s0, 0x820
	v_cmp_gt_u32_e32 vcc, s0, v74
	s_and_saveexec_b64 s[0:1], vcc
	s_cbranch_execz .LBB0_689
	v_lshrrev_b32_e32 v0, 3, v152
	v_lshlrev_b32_e32 v1, 3, v152
	v_or_b32_e32 v79, 0x60, v0
	v_lshrrev_b32_e32 v0, 1, v152
	v_and_b32_e32 v2, 31, v152
	v_and_b32_e32 v76, 56, v1
	v_lshrrev_b32_e32 v1, 4, v152
	v_and_or_b32 v0, v0, 64, v2
	v_lshrrev_b32_e32 v2, 2, v152
	v_bfe_u32 v75, v152, 3, 5
	v_and_b32_e32 v77, 0x7f, v152
	v_and_b32_e32 v1, 8, v1
	s_movk_i32 s3, 0x48
	v_and_b32_e32 v2, 8, v2
	v_mad_u32_u24 v80, v77, s3, v1
	v_mad_u32_u24 v81, v75, s3, v76
	v_mad_u32_u24 v84, v79, s3, v76
	v_and_b32_e32 v3, 0x5f, v152
	v_mad_u32_u24 v86, v0, s3, v2
	s_add_u32 s4, s90, 0x6300000
	s_movk_i32 s8, 0x8000
	v_lshrrev_b32_e32 v78, 1, v1
	v_lshl_add_u32 v82, v81, 1, v71
	v_lshl_add_u32 v83, v80, 1, v71
	v_lshl_add_u32 v85, v84, 1, v71
	v_mad_u32_u24 v87, v3, s3, v2
	v_and_b32_e32 v88, 0xff, v152
	s_addc_u32 s5, s91, 0
	s_lshl_b32 s3, s96, 1
	v_add_u32_e32 v89, 16, v86
	v_add_u32_e32 v90, 32, v86
	v_add_u32_e32 v91, 48, v86
	v_or_b32_e32 v92, 64, v1
	v_or_b32_e32 v93, 64, v76
	s_mov_b64 s[6:7], 0
	s_movk_i32 s14, 0x7ff
	v_mov_b32_e32 v65, 0
	s_mov_b32 s9, -1
	s_mov_b64 s[10:11], 0x400
	s_movk_i32 s15, 0x81f

; __device__ __forceinline__ uint4 gather8p(const u16* p, unsigned off, unsigned s1, unsigned s2) {
;   unsigned v0 = p[off], v1 = p[off + s1], v2 = p[off + s2], v3 = p[off + s2 + s1];
;   unsigned v4 = p[off + 2 * s2], v5 = p[off + 2 * s2 + s1], v6 = p[off + 3 * s2], v7 = p[off + 3 * s2 + s1];
;   return make_uint4(v0 | (v1 << 16), v2 | (v3 << 16), v4 | (v5 << 16), v6 | (v7 << 16));
; template <bool BNN, class AL, class BL>
; __device__ __forceinline__ void gemm_tile_nn(const AL& al, const BL& bl, int K, u16* smem, f32x16 (&acc)[2][2]) {
;     ...
;   for (int kt = 0; kt < nkt; ++kt) {
;     const bool more = (kt + 1 < nkt);
;     if (more) {
;       const int k0 = (kt + 1) << 6;
; #pragma unroll
;       for (int i = 0; i < 4; ++i) {
;         ra[i] = al(lr + 32 * i, k0 + lk);
;         if (BNN) rb[i] = bl(nr, k0 + nk + 16 * i); else rb[i] = bl(lr + 32 * i, k0 + lk);
;       }
;     }
;     const u16* a = sA + (kt & 1) * 128 * LDSS;
;     const u16* b = sB + (kt & 1) * 128 * LDSS;
; #pragma unroll
;     for (int s = 0; s < 4; ++s) {
;       bf16x8 af[2], bfr[2];
; #pragma unroll
;       for (int i = 0; i < 2; ++i)
;         af[i] = *reinterpret_cast<const bf16x8*>(&a[(wm * 64 + i * 32 + (lane & 31)) * LDSS + s * 16 + (lane >> 5) * 8]);
; #pragma unroll
;       for (int j = 0; j < 2; ++j)
;         bfr[j] = *reinterpret_cast<const bf16x8*>(&b[(wn * 64 + j * 32 + (lane & 31)) * LDSS + s * 16 + (lane >> 5) * 8]);
; #pragma unroll
;       for (int i = 0; i < 2; ++i)
; #pragma unroll
;         for (int j = 0; j < 2; ++j)
;           acc[i][j] = __builtin_amdgcn_mfma_f32_32x32x16_bf16(af[i], bfr[j], acc[i][j], 0, 0, 0);
;     }
;     if (more) {
;       u16* a2 = sA + ((kt + 1) & 1) * 128 * LDSS;
;       u16* b2 = sB + ((kt + 1) & 1) * 128 * LDSS;
; #pragma unroll
;       for (int i = 0; i < 4; ++i) {
;         *reinterpret_cast<uint4*>(&a2[(lr + 32 * i) * LDSS + lk]) = ra[i];
;         if (BNN) *reinterpret_cast<uint4*>(&b2[nr * LDSS + nk + 16 * i]) = rb[i];
;         else     *reinterpret_cast<uint4*>(&b2[(lr + 32 * i) * LDSS + lk]) = rb[i];
;       }
;     }
;     __syncthreads();
;   }
.LBB0_687:
	s_and_b32 s18, s17, 0x80
	s_mulk_i32 s18, 0x90
	v_add_u32_e32 v64, s16, v100
	v_add_u32_e32 v120, s18, v71
	v_lshl_add_u64 v[104:105], v[64:65], 1, v[66:67]
	v_lshl_add_u32 v144, v86, 1, v120
	v_lshl_add_u32 v162, v87, 1, v120
	global_load_dwordx4 v[104:107], v[104:105], off
	v_lshl_add_u32 v158, v89, 1, v120
	ds_read_b128 v[108:111], v144
	ds_read_b128 v[112:115], v162 offset:36864
	ds_read_b128 v[116:119], v144 offset:32
	v_lshl_add_u32 v148, v90, 1, v120
	v_lshl_add_u32 v154, v91, 1, v120
	ds_read_b128 v[120:123], v162 offset:41472
	ds_read_b128 v[124:127], v162 offset:36960
	s_waitcnt lgkmcnt(3)
	v_mfma_f32_32x32x16_bf16 v[48:63], v[108:111], v[112:115], v[48:63]
	v_add_u32_e32 v103, s16, v92
	v_ashrrev_i32_e32 v64, 1, v103
	v_mul_lo_u32 v103, v64, v96
	v_or_b32_e32 v64, v103, v77
	v_lshl_add_u64 v[166:167], v[64:65], 1, v[72:73]
	v_add_u32_e32 v64, v64, v96
	v_add_u32_e32 v103, v103, v97
	s_waitcnt lgkmcnt(1)
	v_mfma_f32_32x32x16_bf16 v[32:47], v[108:111], v[120:123], v[32:47]
	ds_read_b128 v[108:111], v144 offset:4608
	ds_read_b128 v[128:131], v162 offset:41504
	ds_read_b128 v[132:135], v162 offset:36896
	ds_read_b128 v[136:139], v162 offset:36928
	v_add_u32_e32 v168, v103, v97
	v_add_u32_e32 v169, v168, v97
	s_addk_i32 s17, 0x80
	s_and_b32 s18, s17, 0x80
	s_mulk_i32 s18, 0x90
	s_waitcnt lgkmcnt(3)
	v_mfma_f32_32x32x16_bf16 v[16:31], v[108:111], v[112:115], v[16:31]
	ds_read_b128 v[112:115], v162 offset:41536
	ds_read_b128 v[140:143], v144 offset:64
	ds_read_b128 v[144:147], v144 offset:96
	ds_read_b128 v[148:151], v148 offset:4608
	ds_read_b128 v[154:157], v154 offset:4608
	ds_read_b128 v[158:161], v158 offset:4608
	ds_read_b128 v[162:165], v162 offset:41568
	v_add_u32_e32 v98, -1, v98
	v_cmp_eq_u32_e32 vcc, 0, v98
	v_mfma_f32_32x32x16_bf16 v[0:15], v[108:111], v[120:123], v[0:15]
	v_lshl_add_u64 v[108:109], v[64:65], 1, v[72:73]
	v_add_u32_e32 v64, v64, v96
	global_load_ushort v170, v[166:167], off
	s_nop 0
	global_load_ushort v166, v[166:167], off offset:1024
	s_nop 0
	global_load_ushort v167, v[108:109], off
	global_load_ushort v171, v[108:109], off offset:1024
	v_lshl_add_u64 v[108:109], v[64:65], 1, v[72:73]
	v_add_u32_e32 v64, v64, v96
	v_lshl_add_u64 v[110:111], v[64:65], 1, v[72:73]
	v_add_u32_e32 v64, s16, v102
	s_waitcnt lgkmcnt(8)
	v_mfma_f32_32x32x16_bf16 v[48:63], v[116:119], v[132:135], v[48:63]
	global_load_ushort v172, v[108:109], off
	global_load_ushort v173, v[108:109], off offset:1024
	global_load_ushort v174, v[110:111], off
	v_lshl_add_u64 v[108:109], v[64:65], 1, v[66:67]
	v_or_b32_e32 v64, v103, v77
	global_load_ushort v175, v[110:111], off offset:1024
	v_add_u32_e32 v103, s18, v71
	global_load_dwordx4 v[108:111], v[108:109], off
	v_mfma_f32_32x32x16_bf16 v[32:47], v[116:119], v[128:131], v[32:47]
	v_lshl_add_u64 v[116:117], v[64:65], 1, v[72:73]
	v_add_u32_e32 v64, v64, v96
	v_lshl_add_u64 v[118:119], v[64:65], 1, v[72:73]
	v_add_u32_e32 v64, v64, v96
	s_waitcnt lgkmcnt(1)
	v_mfma_f32_32x32x16_bf16 v[16:31], v[158:161], v[132:135], v[16:31]
	global_load_ushort v132, v[116:117], off
	global_load_ushort v133, v[116:117], off offset:1024
	global_load_ushort v134, v[118:119], off
	global_load_ushort v135, v[118:119], off offset:1024
	v_lshl_add_u64 v[116:117], v[64:65], 1, v[72:73]
	v_add_u32_e32 v64, v64, v96
	v_lshl_add_u64 v[118:119], v[64:65], 1, v[72:73]
	v_add_u32_e32 v64, s16, v101
	v_mfma_f32_32x32x16_bf16 v[0:15], v[158:161], v[128:131], v[0:15]
	global_load_ushort v128, v[116:117], off
	global_load_ushort v129, v[116:117], off offset:1024
	global_load_ushort v130, v[118:119], off
	global_load_ushort v131, v[118:119], off offset:1024
	v_lshl_add_u64 v[116:117], v[64:65], 1, v[66:67]
	v_or_b32_e32 v64, v168, v77
	v_lshl_add_u64 v[120:121], v[64:65], 1, v[72:73]
	v_add_u32_e32 v64, v64, v96
	v_lshl_add_u64 v[122:123], v[64:65], 1, v[72:73]
	v_add_u32_e32 v64, v64, v96
	v_mfma_f32_32x32x16_bf16 v[48:63], v[140:143], v[136:139], v[48:63]
	global_load_dwordx4 v[116:119], v[116:117], off
	s_nop 0
	global_load_ushort v158, v[120:121], off
	v_mfma_f32_32x32x16_bf16 v[32:47], v[140:143], v[112:115], v[32:47]
	global_load_ushort v140, v[120:121], off offset:1024
	global_load_ushort v141, v[122:123], off
	global_load_ushort v142, v[122:123], off offset:1024
	v_lshl_add_u64 v[120:121], v[64:65], 1, v[72:73]
	v_add_u32_e32 v64, v64, v96
	v_lshl_add_u64 v[122:123], v[64:65], 1, v[72:73]
	v_add_u32_e32 v64, s16, v99
	s_add_i32 s16, s16, 64
	s_or_b64 s[12:13], vcc, s[12:13]
	v_mfma_f32_32x32x16_bf16 v[16:31], v[148:151], v[136:139], v[16:31]
	global_load_ushort v136, v[120:121], off
	global_load_ushort v137, v[120:121], off offset:1024
	global_load_ushort v138, v[122:123], off
	global_load_ushort v139, v[122:123], off offset:1024
	v_lshl_add_u64 v[120:121], v[64:65], 1, v[66:67]
	v_or_b32_e32 v64, v169, v77
	v_lshl_add_u64 v[122:123], v[64:65], 1, v[72:73]
	v_add_u32_e32 v64, v64, v96
	v_mfma_f32_32x32x16_bf16 v[0:15], v[148:151], v[112:115], v[0:15]
	v_lshl_add_u64 v[112:113], v[64:65], 1, v[72:73]
	v_add_u32_e32 v64, v64, v96
	global_load_ushort v143, v[122:123], off
	s_nop 0
	global_load_ushort v122, v[122:123], off offset:1024
	s_nop 0
	global_load_ushort v123, v[112:113], off
	global_load_ushort v148, v[112:113], off offset:1024
	v_lshl_add_u64 v[112:113], v[64:65], 1, v[72:73]
	v_add_u32_e32 v64, v64, v96
	v_lshl_add_u64 v[114:115], v[64:65], 1, v[72:73]
	global_load_ushort v64, v[112:113], off
	global_load_ushort v149, v[112:113], off offset:1024
	global_load_ushort v150, v[114:115], off
	global_load_ushort v151, v[114:115], off offset:1024
	v_mfma_f32_32x32x16_bf16 v[48:63], v[144:147], v[124:127], v[48:63]
	global_load_dwordx4 v[112:115], v[120:121], off
	v_lshl_add_u32 v120, v81, 1, v103
	v_lshl_add_u32 v121, v80, 1, v103
	s_waitcnt vmcnt(35)
; template <bool BNN, class AL, class BL>
; __device__ __forceinline__ void gemm_tile_nn(const AL& al, const BL& bl, int K, u16* smem, f32x16 (&acc)[2][2]) {
;     ...
;   for (int kt = 0; kt < nkt; ++kt) {
;     const bool more = (kt + 1 < nkt);
;     if (more) {
;       const int k0 = (kt + 1) << 6;
; #pragma unroll
;       for (int i = 0; i < 4; ++i) {
;         ra[i] = al(lr + 32 * i, k0 + lk);
;         if (BNN) rb[i] = bl(nr, k0 + nk + 16 * i); else rb[i] = bl(lr + 32 * i, k0 + lk);
;       }
;     }
;     const u16* a = sA + (kt & 1) * 128 * LDSS;
;     const u16* b = sB + (kt & 1) * 128 * LDSS;
; #pragma unroll
;     for (int s = 0; s < 4; ++s) {
;       bf16x8 af[2], bfr[2];
; #pragma unroll
;       for (int i = 0; i < 2; ++i)
;         af[i] = *reinterpret_cast<const bf16x8*>(&a[(wm * 64 + i * 32 + (lane & 31)) * LDSS + s * 16 + (lane >> 5) * 8]);
; #pragma unroll
;       for (int j = 0; j < 2; ++j)
;         bfr[j] = *reinterpret_cast<const bf16x8*>(&b[(wn * 64 + j * 32 + (lane & 31)) * LDSS + s * 16 + (lane >> 5) * 8]);
; #pragma unroll
;       for (int i = 0; i < 2; ++i)
; #pragma unroll
;         for (int j = 0; j < 2; ++j)
;           acc[i][j] = __builtin_amdgcn_mfma_f32_32x32x16_bf16(af[i], bfr[j], acc[i][j], 0, 0, 0);
;     }
;     if (more) {
;       u16* a2 = sA + ((kt + 1) & 1) * 128 * LDSS;
;       u16* b2 = sB + ((kt + 1) & 1) * 128 * LDSS;
; #pragma unroll
;       for (int i = 0; i < 4; ++i) {
;         *reinterpret_cast<uint4*>(&a2[(lr + 32 * i) * LDSS + lk]) = ra[i];
;         if (BNN) *reinterpret_cast<uint4*>(&b2[nr * LDSS + nk + 16 * i]) = rb[i];
;         else     *reinterpret_cast<uint4*>(&b2[(lr + 32 * i) * LDSS + lk]) = rb[i];
;       }
;     }
;     __syncthreads();
;   }
; __device__ __forceinline__ void nn_phase(const Params& P, int set, u16* smem) {
;     ...
;     auto al = [=](int r, int k) { return ldg16(Ab + (unsigned)(r * lda + k)); };
;     auto bl = [=](int n, int k) { return gather8p(Bb, (unsigned)((k >> 1) * s2 + n), s1, s2); };
;     f32x16 acc[2][2];
;     gemm_tile_nn<true>(al, bl, K, smem, acc);
;     ACC_FOREACH({ Cb[(unsigned)((row >> 1) * e2 + (row & 1) * e1 + col)] = f2bf(v); })
	ds_write_b128 v120, v[104:107]
	s_waitcnt vmcnt(33)
	v_lshl_or_b32 v104, v166, 16, v170
	s_waitcnt lgkmcnt(1)
	v_mfma_f32_32x32x16_bf16 v[32:47], v[144:147], v[162:165], v[32:47]
	s_waitcnt vmcnt(31)
	v_lshl_or_b32 v105, v171, 16, v167
	s_waitcnt vmcnt(29)
	v_lshl_or_b32 v106, v173, 16, v172
	s_waitcnt vmcnt(27)
	v_lshl_or_b32 v107, v175, 16, v174
	v_mfma_f32_32x32x16_bf16 v[16:31], v[154:157], v[124:127], v[16:31]
	ds_write_b128 v121, v[104:107] offset:36864
	s_waitcnt vmcnt(26)
	ds_write_b128 v120, v[108:111] offset:4608
	v_lshl_add_u32 v124, v84, 1, v103
	s_waitcnt vmcnt(24)
	v_lshl_or_b32 v104, v133, 16, v132
	v_mfma_f32_32x32x16_bf16 v[0:15], v[154:157], v[162:165], v[0:15]
	s_waitcnt vmcnt(22)
	v_lshl_or_b32 v105, v135, 16, v134
	s_waitcnt vmcnt(20)
	v_lshl_or_b32 v106, v129, 16, v128
	s_waitcnt vmcnt(18)
	v_lshl_or_b32 v107, v131, 16, v130
	ds_write_b128 v121, v[104:107] offset:36896
	s_waitcnt vmcnt(17)
	ds_write_b128 v120, v[116:119] offset:9216
	s_waitcnt vmcnt(15)
	v_lshl_or_b32 v104, v140, 16, v158
	s_waitcnt vmcnt(13)
	v_lshl_or_b32 v105, v142, 16, v141
	s_waitcnt vmcnt(11)
	v_lshl_or_b32 v106, v137, 16, v136
	s_waitcnt vmcnt(9)
	v_lshl_or_b32 v107, v139, 16, v138
	ds_write_b128 v121, v[104:107] offset:36928
	s_waitcnt vmcnt(0)
	ds_write_b128 v124, v[112:115]
	v_lshl_or_b32 v104, v122, 16, v143
	v_lshl_or_b32 v105, v148, 16, v123
	v_lshl_or_b32 v106, v149, 16, v64
	v_lshl_or_b32 v107, v151, 16, v150
	ds_write_b128 v121, v[104:107] offset:36960
	s_waitcnt lgkmcnt(0)
	s_barrier
	s_andn2_b64 exec, exec, s[12:13]
	s_cbranch_execnz .LBB0_687
	s_or_b64 exec, exec, s[12:13]
	v_lshl_add_u32 v72, v86, 1, v103
	ds_read_b128 v[96:99], v72
	v_lshl_add_u32 v73, v87, 1, v103
	ds_read_b128 v[104:107], v73 offset:36864
	ds_read_b128 v[108:111], v72 offset:32
	ds_read_b128 v[116:119], v73 offset:41472
	ds_read_b128 v[112:115], v72 offset:4608
	ds_read_b128 v[120:123], v73 offset:36960
	v_lshlrev_b32_e32 v64, 1, v70
	v_lshl_add_u64 v[66:67], v[68:69], 0, v[64:65]
	v_lshl_add_u32 v64, v90, 1, v103
	s_waitcnt lgkmcnt(4)
	v_mfma_f32_32x32x16_bf16 v[48:63], v[96:99], v[104:107], v[48:63]
	v_lshl_add_u32 v70, v89, 1, v103
	v_lshl_add_u32 v68, v91, 1, v103
	v_add_u32_e32 v74, 0x1c0, v74
	v_cmp_lt_i32_e32 vcc, s15, v74
	s_or_b64 s[6:7], vcc, s[6:7]
	s_waitcnt lgkmcnt(2)
	v_mfma_f32_32x32x16_bf16 v[32:47], v[96:99], v[116:119], v[32:47]
	ds_read_b128 v[96:99], v73 offset:36896
	ds_read_b128 v[124:127], v73 offset:36928
	ds_read_b128 v[128:131], v73 offset:41504
	ds_read_b128 v[132:135], v73 offset:41536
	ds_read_b128 v[136:139], v72 offset:64
	ds_read_b128 v[140:143], v72 offset:96
	ds_read_b128 v[100:103], v64 offset:4608
	ds_read_b128 v[144:147], v68 offset:4608
	ds_read_b128 v[148:151], v70 offset:4608
	ds_read_b128 v[154:157], v73 offset:41568
	v_mov_b32_e32 v64, v88
	s_waitcnt lgkmcnt(0)
	s_barrier
	v_mfma_f32_32x32x16_bf16 v[48:63], v[108:111], v[96:99], v[48:63]
	v_ashrrev_i32_e32 v68, 1, v64
	v_and_b32_e32 v70, 0xffffffc0, v68
	v_lshrrev_b32_e32 v68, 3, v64
	v_and_b32_e32 v72, 4, v68
	v_and_b32_e32 v73, 0x5f, v64
	v_or_b32_e32 v64, v72, v70
	v_ashrrev_i32_e32 v64, 1, v64
	v_mfma_f32_32x32x16_bf16 v[48:63], v[136:139], v[124:127], v[48:63]
	v_mul_lo_u32 v158, v64, v95
	v_or_b32_e32 v64, v158, v73
	v_lshl_add_u64 v[68:69], v[64:65], 1, v[66:67]
	v_mfma_f32_32x32x16_bf16 v[48:63], v[140:143], v[120:123], v[48:63]
	v_mfma_f32_32x32x16_bf16 v[16:31], v[112:115], v[104:107], v[16:31]
	s_nop 10
	v_cvt_pk_bf16_f32 v48, v48, s0
	global_store_short v[68:69], v48, off
	v_add_u32_e32 v69, v158, v94
	v_or_b32_e32 v64, v69, v73
	v_cvt_pk_bf16_f32 v68, v49, s0
	v_lshl_add_u64 v[48:49], v[64:65], 1, v[66:67]
	global_store_short v[48:49], v68, off
	v_or_b32_e32 v68, 2, v70
	v_or_b32_e32 v48, v68, v72
	v_ashrrev_i32_e32 v48, 1, v48
	v_mul_lo_u32 v104, v48, v95
	v_or_b32_e32 v64, v104, v73
	v_cvt_pk_bf16_f32 v50, v50, s0
	v_lshl_add_u64 v[48:49], v[64:65], 1, v[66:67]
	global_store_short v[48:49], v50, off
	v_cvt_pk_bf16_f32 v50, v51, s0
	v_add_u32_e32 v51, v104, v94
	v_or_b32_e32 v64, v51, v73
	v_lshl_add_u64 v[48:49], v[64:65], 1, v[66:67]
	global_store_short v[48:49], v50, off
	v_or_b32_e32 v50, 8, v72
	v_or_b32_e32 v48, v50, v70
	v_ashrrev_i32_e32 v48, 1, v48
	v_mfma_f32_32x32x16_bf16 v[16:31], v[148:151], v[96:99], v[16:31]
	v_mul_lo_u32 v96, v48, v95
	v_or_b32_e32 v64, v96, v73
	v_cvt_pk_bf16_f32 v52, v52, s0
	v_lshl_add_u64 v[48:49], v[64:65], 1, v[66:67]
	global_store_short v[48:49], v52, off
	v_cvt_pk_bf16_f32 v52, v53, s0
	v_add_u32_e32 v53, v96, v94
	v_or_b32_e32 v64, v53, v73
	v_lshl_add_u64 v[48:49], v[64:65], 1, v[66:67]
	global_store_short v[48:49], v52, off
	v_or_b32_e32 v48, v50, v68
	v_ashrrev_i32_e32 v48, 1, v48
	v_cvt_pk_bf16_f32 v52, v54, s0
	v_mul_lo_u32 v54, v48, v95
	v_or_b32_e32 v64, v54, v73
	v_lshl_add_u64 v[48:49], v[64:65], 1, v[66:67]
	global_store_short v[48:49], v52, off
	v_cvt_pk_bf16_f32 v52, v55, s0
	v_add_u32_e32 v55, v54, v94
	v_or_b32_e32 v64, v55, v73
	v_lshl_add_u64 v[48:49], v[64:65], 1, v[66:67]
	global_store_short v[48:49], v52, off
	v_or_b32_e32 v52, 16, v72
	v_or_b32_e32 v48, v52, v70
	v_ashrrev_i32_e32 v48, 1, v48
	v_mul_lo_u32 v97, v48, v95
	v_or_b32_e32 v64, v97, v73
	v_cvt_pk_bf16_f32 v56, v56, s0
	v_lshl_add_u64 v[48:49], v[64:65], 1, v[66:67]
	global_store_short v[48:49], v56, off
	v_cvt_pk_bf16_f32 v56, v57, s0
	v_add_u32_e32 v57, v97, v94
	v_or_b32_e32 v64, v57, v73
	v_lshl_add_u64 v[48:49], v[64:65], 1, v[66:67]
	global_store_short v[48:49], v56, off
	v_or_b32_e32 v48, v52, v68
	v_mfma_f32_32x32x16_bf16 v[32:47], v[108:111], v[128:131], v[32:47]
	v_ashrrev_i32_e32 v48, 1, v48
	v_cvt_pk_bf16_f32 v56, v58, s0
; __device__ __forceinline__ void nn_phase(const Params& P, int set, u16* smem) {
;     ...
;     auto al = [=](int r, int k) { return ldg16(Ab + (unsigned)(r * lda + k)); };
;     auto bl = [=](int n, int k) { return gather8p(Bb, (unsigned)((k >> 1) * s2 + n), s1, s2); };
;     f32x16 acc[2][2];
;     gemm_tile_nn<true>(al, bl, K, smem, acc);
;     ACC_FOREACH({ Cb[(unsigned)((row >> 1) * e2 + (row & 1) * e1 + col)] = f2bf(v); })
	v_mul_lo_u32 v58, v48, v95
	v_or_b32_e32 v64, v58, v73
	v_lshl_add_u64 v[48:49], v[64:65], 1, v[66:67]
	global_store_short v[48:49], v56, off
	v_cvt_pk_bf16_f32 v56, v59, s0
	v_add_u32_e32 v59, v58, v94
	v_or_b32_e32 v64, v59, v73
	v_lshl_add_u64 v[48:49], v[64:65], 1, v[66:67]
	global_store_short v[48:49], v56, off
	v_or_b32_e32 v56, 24, v72
	v_mfma_f32_32x32x16_bf16 v[32:47], v[136:139], v[132:135], v[32:47]
	v_or_b32_e32 v48, v56, v70
	v_ashrrev_i32_e32 v48, 1, v48
	v_mul_lo_u32 v98, v48, v95
	v_or_b32_e32 v64, v98, v73
	v_cvt_pk_bf16_f32 v60, v60, s0
	v_lshl_add_u64 v[48:49], v[64:65], 1, v[66:67]
	global_store_short v[48:49], v60, off
	v_cvt_pk_bf16_f32 v60, v61, s0
	v_add_u32_e32 v61, v98, v94
	v_or_b32_e32 v64, v61, v73
	v_lshl_add_u64 v[48:49], v[64:65], 1, v[66:67]
	v_mfma_f32_32x32x16_bf16 v[32:47], v[140:143], v[154:157], v[32:47]
	global_store_short v[48:49], v60, off
	v_or_b32_e32 v48, v56, v68
	v_ashrrev_i32_e32 v48, 1, v48
	v_cvt_pk_bf16_f32 v60, v62, s0
	v_mul_lo_u32 v62, v48, v95
	v_or_b32_e32 v64, v62, v73
	v_lshl_add_u64 v[48:49], v[64:65], 1, v[66:67]
	global_store_short v[48:49], v60, off
	v_cvt_pk_bf16_f32 v60, v63, s0
	v_add_u32_e32 v63, v62, v94
	v_or_b32_e32 v64, v63, v73
	v_lshl_add_u64 v[48:49], v[64:65], 1, v[66:67]
	v_add_u32_e32 v64, v158, v73
	global_store_short v[48:49], v60, off
	v_cvt_pk_bf16_f32 v32, v32, s0
	v_lshl_add_u64 v[48:49], v[64:65], 1, v[66:67]
	v_add_u32_e32 v64, v69, v73
	global_store_short v[48:49], v32, off offset:64
	v_cvt_pk_bf16_f32 v48, v33, s0
	v_lshl_add_u64 v[32:33], v[64:65], 1, v[66:67]
	v_add_u32_e32 v64, v104, v73
	global_store_short v[32:33], v48, off offset:64
	v_cvt_pk_bf16_f32 v34, v34, s0
	v_lshl_add_u64 v[32:33], v[64:65], 1, v[66:67]
	v_add_u32_e32 v64, v51, v73
	global_store_short v[32:33], v34, off offset:64
	v_cvt_pk_bf16_f32 v34, v35, s0
	v_lshl_add_u64 v[32:33], v[64:65], 1, v[66:67]
	v_add_u32_e32 v64, v96, v73
	global_store_short v[32:33], v34, off offset:64
	v_cvt_pk_bf16_f32 v34, v36, s0
	v_lshl_add_u64 v[32:33], v[64:65], 1, v[66:67]
	v_add_u32_e32 v64, v53, v73
	v_mfma_f32_32x32x16_bf16 v[16:31], v[100:103], v[124:127], v[16:31]
	global_store_short v[32:33], v34, off offset:64
	v_cvt_pk_bf16_f32 v34, v37, s0
	v_lshl_add_u64 v[32:33], v[64:65], 1, v[66:67]
	v_add_u32_e32 v64, v54, v73
	global_store_short v[32:33], v34, off offset:64
	v_cvt_pk_bf16_f32 v34, v38, s0
	v_lshl_add_u64 v[32:33], v[64:65], 1, v[66:67]
	v_add_u32_e32 v64, v55, v73
	global_store_short v[32:33], v34, off offset:64
	v_cvt_pk_bf16_f32 v34, v39, s0
	v_lshl_add_u64 v[32:33], v[64:65], 1, v[66:67]
	v_add_u32_e32 v64, v97, v73
	global_store_short v[32:33], v34, off offset:64
	v_cvt_pk_bf16_f32 v34, v40, s0
	v_lshl_add_u64 v[32:33], v[64:65], 1, v[66:67]
	v_add_u32_e32 v64, v57, v73
	global_store_short v[32:33], v34, off offset:64
	v_cvt_pk_bf16_f32 v34, v41, s0
	v_lshl_add_u64 v[32:33], v[64:65], 1, v[66:67]
	v_add_u32_e32 v64, v58, v73
	global_store_short v[32:33], v34, off offset:64
	v_cvt_pk_bf16_f32 v34, v42, s0
	v_lshl_add_u64 v[32:33], v[64:65], 1, v[66:67]
	v_add_u32_e32 v64, v59, v73
	global_store_short v[32:33], v34, off offset:64
	v_cvt_pk_bf16_f32 v34, v43, s0
	v_lshl_add_u64 v[32:33], v[64:65], 1, v[66:67]
	v_add_u32_e32 v64, v98, v73
	global_store_short v[32:33], v34, off offset:64
	v_cvt_pk_bf16_f32 v34, v44, s0
	v_lshl_add_u64 v[32:33], v[64:65], 1, v[66:67]
	v_add_u32_e32 v64, v61, v73
	v_mfma_f32_32x32x16_bf16 v[16:31], v[144:147], v[120:123], v[16:31]
	global_store_short v[32:33], v34, off offset:64
	v_cvt_pk_bf16_f32 v34, v45, s0
	v_lshl_add_u64 v[32:33], v[64:65], 1, v[66:67]
	v_add_u32_e32 v64, v62, v73
	global_store_short v[32:33], v34, off offset:64
	v_cvt_pk_bf16_f32 v34, v46, s0
	v_lshl_add_u64 v[32:33], v[64:65], 1, v[66:67]
	v_add_u32_e32 v64, v63, v73
	global_store_short v[32:33], v34, off offset:64
	v_cvt_pk_bf16_f32 v34, v47, s0
	v_lshl_add_u64 v[32:33], v[64:65], 1, v[66:67]
	global_store_short v[32:33], v34, off offset:64
	v_or_b32_e32 v34, 32, v70
	v_or_b32_e32 v32, v34, v72
	v_ashrrev_i32_e32 v32, 1, v32
	v_mul_lo_u32 v35, v32, v95
	v_or_b32_e32 v64, v35, v73
	v_cvt_pk_bf16_f32 v16, v16, s0
	v_lshl_add_u64 v[32:33], v[64:65], 1, v[66:67]
	global_store_short v[32:33], v16, off
	v_add_u32_e32 v33, v35, v94
	v_or_b32_e32 v64, v33, v73
	v_cvt_pk_bf16_f32 v32, v17, s0
	v_lshl_add_u64 v[16:17], v[64:65], 1, v[66:67]
	global_store_short v[16:17], v32, off
	v_or_b32_e32 v32, 34, v70
	v_or_b32_e32 v16, v32, v72
	v_ashrrev_i32_e32 v16, 1, v16
	v_mul_lo_u32 v36, v16, v95
	v_or_b32_e32 v64, v36, v73
	v_cvt_pk_bf16_f32 v18, v18, s0
	v_lshl_add_u64 v[16:17], v[64:65], 1, v[66:67]
	global_store_short v[16:17], v18, off
	v_cvt_pk_bf16_f32 v18, v19, s0
	v_add_u32_e32 v19, v36, v94
	v_or_b32_e32 v64, v19, v73
	v_lshl_add_u64 v[16:17], v[64:65], 1, v[66:67]
	global_store_short v[16:17], v18, off
	v_or_b32_e32 v16, v50, v34
	v_ashrrev_i32_e32 v16, 1, v16
	v_cvt_pk_bf16_f32 v18, v20, s0
	v_mul_lo_u32 v20, v16, v95
	v_or_b32_e32 v64, v20, v73
	v_lshl_add_u64 v[16:17], v[64:65], 1, v[66:67]
; __device__ __forceinline__ void nn_phase(const Params& P, int set, u16* smem) {
;     ...
;     auto al = [=](int r, int k) { return ldg16(Ab + (unsigned)(r * lda + k)); };
;     auto bl = [=](int n, int k) { return gather8p(Bb, (unsigned)((k >> 1) * s2 + n), s1, s2); };
;     f32x16 acc[2][2];
;     gemm_tile_nn<true>(al, bl, K, smem, acc);
;     ACC_FOREACH({ Cb[(unsigned)((row >> 1) * e2 + (row & 1) * e1 + col)] = f2bf(v); })
	global_store_short v[16:17], v18, off
	v_cvt_pk_bf16_f32 v18, v21, s0
	v_add_u32_e32 v21, v20, v94
	v_or_b32_e32 v64, v21, v73
	v_lshl_add_u64 v[16:17], v[64:65], 1, v[66:67]
	global_store_short v[16:17], v18, off
	v_or_b32_e32 v16, v50, v32
	v_ashrrev_i32_e32 v16, 1, v16
	v_cvt_pk_bf16_f32 v18, v22, s0
	v_mul_lo_u32 v22, v16, v95
	v_or_b32_e32 v64, v22, v73
	v_lshl_add_u64 v[16:17], v[64:65], 1, v[66:67]
	global_store_short v[16:17], v18, off
	v_cvt_pk_bf16_f32 v18, v23, s0
	v_add_u32_e32 v23, v22, v94
	v_or_b32_e32 v64, v23, v73
	v_lshl_add_u64 v[16:17], v[64:65], 1, v[66:67]
	v_mfma_f32_32x32x16_bf16 v[0:15], v[112:115], v[116:119], v[0:15]
	global_store_short v[16:17], v18, off
	v_or_b32_e32 v16, v52, v34
	v_ashrrev_i32_e32 v16, 1, v16
	v_cvt_pk_bf16_f32 v18, v24, s0
	v_mul_lo_u32 v24, v16, v95
	v_or_b32_e32 v64, v24, v73
	v_lshl_add_u64 v[16:17], v[64:65], 1, v[66:67]
	global_store_short v[16:17], v18, off
	v_cvt_pk_bf16_f32 v18, v25, s0
	v_add_u32_e32 v25, v24, v94
	v_or_b32_e32 v64, v25, v73
	v_lshl_add_u64 v[16:17], v[64:65], 1, v[66:67]
	v_mfma_f32_32x32x16_bf16 v[0:15], v[148:151], v[128:131], v[0:15]
	global_store_short v[16:17], v18, off
	v_or_b32_e32 v16, v52, v32
	v_ashrrev_i32_e32 v16, 1, v16
	v_cvt_pk_bf16_f32 v18, v26, s0
	v_mul_lo_u32 v26, v16, v95
	v_or_b32_e32 v64, v26, v73
	v_lshl_add_u64 v[16:17], v[64:65], 1, v[66:67]
	global_store_short v[16:17], v18, off
	v_cvt_pk_bf16_f32 v18, v27, s0
	v_add_u32_e32 v27, v26, v94
	v_or_b32_e32 v64, v27, v73
	v_lshl_add_u64 v[16:17], v[64:65], 1, v[66:67]
	v_mfma_f32_32x32x16_bf16 v[0:15], v[100:103], v[132:135], v[0:15]
	global_store_short v[16:17], v18, off
	v_or_b32_e32 v16, v56, v34
	v_ashrrev_i32_e32 v16, 1, v16
	v_cvt_pk_bf16_f32 v18, v28, s0
	v_mul_lo_u32 v28, v16, v95
	v_or_b32_e32 v64, v28, v73
	v_lshl_add_u64 v[16:17], v[64:65], 1, v[66:67]
	global_store_short v[16:17], v18, off
	v_cvt_pk_bf16_f32 v18, v29, s0
	v_add_u32_e32 v29, v28, v94
	v_or_b32_e32 v64, v29, v73
	v_lshl_add_u64 v[16:17], v[64:65], 1, v[66:67]
	v_mfma_f32_32x32x16_bf16 v[0:15], v[144:147], v[154:157], v[0:15]
	global_store_short v[16:17], v18, off
	v_or_b32_e32 v16, v56, v32
	v_ashrrev_i32_e32 v16, 1, v16
	v_cvt_pk_bf16_f32 v18, v30, s0
	v_mul_lo_u32 v30, v16, v95
	v_or_b32_e32 v64, v30, v73
	v_lshl_add_u64 v[16:17], v[64:65], 1, v[66:67]
	global_store_short v[16:17], v18, off
	v_cvt_pk_bf16_f32 v18, v31, s0
	v_add_u32_e32 v31, v30, v94
	v_or_b32_e32 v64, v31, v73
	v_lshl_add_u64 v[16:17], v[64:65], 1, v[66:67]
	v_add_u32_e32 v64, v35, v73
	global_store_short v[16:17], v18, off
	v_cvt_pk_bf16_f32 v0, v0, s0
	v_lshl_add_u64 v[16:17], v[64:65], 1, v[66:67]
	v_add_u32_e32 v64, v33, v73
	global_store_short v[16:17], v0, off offset:64
	v_cvt_pk_bf16_f32 v16, v1, s0
	v_lshl_add_u64 v[0:1], v[64:65], 1, v[66:67]
	v_add_u32_e32 v64, v36, v73
	global_store_short v[0:1], v16, off offset:64
	v_cvt_pk_bf16_f32 v2, v2, s0
	v_lshl_add_u64 v[0:1], v[64:65], 1, v[66:67]
	v_add_u32_e32 v64, v19, v73
	global_store_short v[0:1], v2, off offset:64
	v_cvt_pk_bf16_f32 v2, v3, s0
	v_lshl_add_u64 v[0:1], v[64:65], 1, v[66:67]
	v_add_u32_e32 v64, v20, v73
	global_store_short v[0:1], v2, off offset:64
	v_cvt_pk_bf16_f32 v2, v4, s0
	v_lshl_add_u64 v[0:1], v[64:65], 1, v[66:67]
	v_add_u32_e32 v64, v21, v73
	global_store_short v[0:1], v2, off offset:64
	v_cvt_pk_bf16_f32 v2, v5, s0
	v_lshl_add_u64 v[0:1], v[64:65], 1, v[66:67]
	v_add_u32_e32 v64, v22, v73
	global_store_short v[0:1], v2, off offset:64
	v_cvt_pk_bf16_f32 v2, v6, s0
	v_lshl_add_u64 v[0:1], v[64:65], 1, v[66:67]
	v_add_u32_e32 v64, v23, v73
	global_store_short v[0:1], v2, off offset:64
	v_cvt_pk_bf16_f32 v2, v7, s0
	v_lshl_add_u64 v[0:1], v[64:65], 1, v[66:67]
	v_add_u32_e32 v64, v24, v73
	global_store_short v[0:1], v2, off offset:64
	v_cvt_pk_bf16_f32 v2, v8, s0
	v_lshl_add_u64 v[0:1], v[64:65], 1, v[66:67]
	v_add_u32_e32 v64, v25, v73
	global_store_short v[0:1], v2, off offset:64
	v_cvt_pk_bf16_f32 v2, v9, s0
	v_lshl_add_u64 v[0:1], v[64:65], 1, v[66:67]
	v_add_u32_e32 v64, v26, v73
	global_store_short v[0:1], v2, off offset:64
	v_cvt_pk_bf16_f32 v2, v10, s0
	v_lshl_add_u64 v[0:1], v[64:65], 1, v[66:67]
	v_add_u32_e32 v64, v27, v73
	global_store_short v[0:1], v2, off offset:64
	v_cvt_pk_bf16_f32 v2, v11, s0
	v_lshl_add_u64 v[0:1], v[64:65], 1, v[66:67]
	v_add_u32_e32 v64, v28, v73
	global_store_short v[0:1], v2, off offset:64
	v_cvt_pk_bf16_f32 v2, v12, s0
	v_lshl_add_u64 v[0:1], v[64:65], 1, v[66:67]
	v_add_u32_e32 v64, v29, v73
	global_store_short v[0:1], v2, off offset:64
	v_cvt_pk_bf16_f32 v2, v13, s0
	v_lshl_add_u64 v[0:1], v[64:65], 1, v[66:67]
	v_add_u32_e32 v64, v30, v73
	global_store_short v[0:1], v2, off offset:64
	v_cvt_pk_bf16_f32 v2, v14, s0
	v_lshl_add_u64 v[0:1], v[64:65], 1, v[66:67]
	v_add_u32_e32 v64, v31, v73
	global_store_short v[0:1], v2, off offset:64
	v_cvt_pk_bf16_f32 v2, v15, s0
	v_lshl_add_u64 v[0:1], v[64:65], 1, v[66:67]
	global_store_short v[0:1], v2, off offset:64
	s_andn2_b64 exec, exec, s[6:7]
	s_cbranch_execnz .LBB0_682
